# v17: prompt attention items permuted so a CU takes items of batch cu%8 (XCD-local K/V)
# speedup vs baseline: 1.0035x; 1.0035x over previous
.LBB0_968:
	s_mulk_i32 s72, 0xf10
	s_add_i32 s78, s76, s72
	s_cmpk_gt_i32 s78, 0x2327
	s_mov_b64 s[40:41], -1
	s_cbranch_scc1 .LBB0_959
	s_and_b32 s98, s78, 7
	s_lshr_b32 s99, s78, 3
	s_lshl_b32 s100, s98, 9
	s_or_b32 s100, s100, s99
	s_lshl_b32 s98, s98, 10
	s_add_i32 s98, s98, s99
	s_addk_i32 s98, 0xe00
	s_cmpk_lt_u32 s99, 0x200
	s_cselect_b32 s78, s100, s98
	s_cmpk_gt_i32 s78, 0xfff
	v_lshlrev_b32_e32 v2, 1, v184
	s_cbranch_scc0 .LBB0_980
	s_add_i32 s40, s78, 0xfffff000
	s_lshr_b32 s88, s40, 10
	s_and_b32 s41, s78, 0x7f
	s_lshl_b32 s72, s88, 12
	s_lshl_b32 s40, s41, 5
	s_or_b32 s72, s72, s40
	v_or_b32_e32 v4, s72, v1
	s_bfe_u32 s85, s78, 0x30007
	v_mul_lo_u32 v4, v4, s59
	v_mov_b32_e32 v5, v3
	v_lshl_add_u64 v[4:5], v[4:5], 1, s[48:49]
	s_lshl_b32 s72, s85, 7
	s_load_dwordx2 s[86:87], s[0:1], 0x70
	v_lshl_add_u64 v[100:101], v[4:5], 0, s[72:73]
	s_lshl_b32 s72, s78, 10
	s_and_b32 s72, s72, 0x80000
	s_lshl_b32 s88, s88, 20
	s_or_b32 s72, s88, s72
	s_lshl_b32 s88, s85, 2
	v_mov_b32_e32 v4, s88
	v_lshl_add_u64 v[6:7], v[100:101], 0, v[2:3]
	s_waitcnt lgkmcnt(0)
	global_load_dword v9, v4, s[86:87]
	global_load_dwordx4 v[52:55], v[6:7], off
	global_load_dwordx4 v[56:59], v[6:7], off offset:32
	global_load_dwordx4 v[60:63], v[6:7], off offset:64
	global_load_dwordx4 v[64:67], v[6:7], off offset:96
	v_sub_u32_e64 v6, 4, s41 clamp
	v_add_u32_e32 v6, s41, v6
	v_add_u32_e32 v6, -4, v6
	v_ashrrev_i32_e32 v7, 31, v6
	v_lshl_add_u64 v[4:5], v[188:189], 0, s[72:73]
	v_lshlrev_b64 v[6:7], 12, v[6:7]
	v_lshl_add_u64 v[4:5], v[4:5], 0, v[6:7]
	global_load_dwordx4 v[80:83], v[4:5], off offset:3072
	global_load_dwordx4 v[76:79], v[4:5], off offset:2048
	global_load_dwordx4 v[72:75], v[4:5], off offset:1024
	global_load_dwordx4 v[68:71], v[4:5], off
	s_mov_b32 s76, s78
	s_mov_b32 s77, s73
	s_and_b32 s76, s76, 0x7f
	v_and_b32_e32 v11, 64, v185
	s_add_i32 s85, s85, 1
	v_cmp_lt_u64_e64 s[86:87], s[76:77], 4
	v_xor_b32_e32 v10, 32, v185
	v_add_u32_e32 v11, 64, v11
	v_cvt_f32_ubyte0_e32 v12, s85
	s_and_b64 s[86:87], s[86:87], exec
	v_or_b32_e32 v13, s40, v1
	v_cmp_lt_i32_e32 vcc, v10, v11
	v_exp_f32_e64 v11, -v12
	s_cselect_b32 s76, s76, 4
	s_min_u32 s87, s41, 4
	v_cvt_f32_u32_e32 v12, v13
	s_lshl_b32 s79, s76, 12
	s_sub_i32 s76, s41, s87
	s_ashr_i32 s77, s76, 31
	s_add_u32 s85, s79, 0xffffc000
	s_add_u32 s86, s79, 0x1000
	s_lshl_b64 s[76:77], s[76:77], 12
	v_cndmask_b32_e32 v10, v185, v10, vcc
	v_mul_f32_e32 v102, 0x3fb8aa3b, v11
	s_add_u32 s76, s76, s72
	v_mov_b32_e32 v18, v3
	v_mov_b32_e32 v19, v3
	v_mov_b32_e32 v4, v3
	v_mov_b32_e32 v5, v3
	v_mov_b32_e32 v6, v3
	v_mov_b32_e32 v7, v3
	v_mov_b32_e32 v8, v3
	v_lshlrev_b32_e32 v103, 2, v10
	v_mul_f32_e32 v124, v102, v12
	s_addc_u32 s77, s77, 0
	s_lshl_b32 s41, s87, 5
	v_mov_b32_e32 v10, v3
	v_mov_b32_e32 v11, v3
	v_mov_b32_e32 v12, v3
	v_mov_b32_e32 v13, v3
	v_mov_b32_e32 v14, v3
	v_mov_b32_e32 v15, v3
	v_mov_b32_e32 v16, v3
	v_mov_b32_e32 v17, v3
	v_pk_mul_f32 v[104:105], v[102:103], v[190:191] op_sel_hi:[0,1]
	v_pk_mul_f32 v[106:107], v[102:103], v[192:193] op_sel_hi:[0,1]
	v_pk_mul_f32 v[108:109], v[102:103], v[194:195] op_sel_hi:[0,1]
	v_pk_mul_f32 v[110:111], v[102:103], v[196:197] op_sel_hi:[0,1]
	v_pk_mul_f32 v[112:113], v[102:103], v[198:199] op_sel_hi:[0,1]
	v_pk_mul_f32 v[114:115], v[102:103], v[200:201] op_sel_hi:[0,1]
	v_pk_mul_f32 v[116:117], v[102:103], v[202:203] op_sel_hi:[0,1]
	v_pk_mul_f32 v[118:119], v[102:103], v[204:205] op_sel_hi:[0,1]
	v_lshl_add_u64 v[120:121], v[208:209], 0, s[76:77]
	s_sub_i32 s72, s40, s41
	v_lshl_add_u64 v[122:123], v[212:213], 0, s[76:77]
	v_mov_b32_e32 v125, 1.0
	s_mov_b64 s[40:41], 0
	s_waitcnt vmcnt(8)
	v_mul_f32_e32 v126, 0x3fb8aa3b, v9
	v_mov_b32_e32 v9, v3
	v_mov_b64_e32 v[34:35], v[18:19]
	v_mov_b64_e32 v[32:33], v[16:17]
	v_mov_b64_e32 v[30:31], v[14:15]
	v_mov_b64_e32 v[28:29], v[12:13]
	v_mov_b64_e32 v[26:27], v[10:11]
	v_mov_b64_e32 v[24:25], v[8:9]
	v_mov_b64_e32 v[22:23], v[6:7]
	v_mov_b64_e32 v[20:21], v[4:5]
	s_branch .LBB0_972

; #define REPS(k) for (int rep_ = 0, nrep_ = 1 + ((DUP_MASK >> (k)) & 1); rep_ < nrep_; ++rep_)
; #define SEAM(k) do { if (IN(k) && IN((k) + 1)) { if (P.ph_lo < 0) grid.sync(); else xcd_barrier(xbar); } } while (0)
; __global__ void __launch_bounds__(512, 2) fwd_kernel(Params P) {
;     ...
;     constexpr int ATT_SPLIT = 9000, ATT_TOTAL = 12288;
;     if (IN(3)) REPS(3) {
;         if (cu >= 16) for (int gt = (cu - 16) * 512 + tid; gt < 131072; gt += (G - 16) * 512) hgrn_scan(HST, HDV, P.out, gt, DRY);
;         if (cu < 16) { SchedUpS S{512, NPJ, 128 + (cu >> 2), cu & 3, (const char*)PROJ, (const char*)WT_UP}; EpiUp E{PROJ, DRY}; pg8::gemm_phase(lds, S, E); }
;         ATT_RUN(0, ATT_SPLIT, 1);
;     }
;     SEAM(3);
;     if (IN(4)) REPS(4) {
;         if (cu < 16) { SchedOne S{1024, NPJ, 128 + (cu >> 2), cu & 3, (const char*)(PROJ + C_MIX), (const char*)WT_O}; EpiRes E{PROJ, XN, 1024}; pg8::gemm_phase(lds, S, E); }
;         ATT_RUN(ATT_SPLIT, ATT_TOTAL, 2);
.LBB0_1078:
	s_mul_i32 s40, s74, 0xf20
	s_add_i32 s76, s40, s68
	s_addk_i32 s76, 0x2328
	s_cmpk_gt_i32 s76, 0x2fff
	s_mov_b64 s[40:41], -1
	s_cbranch_scc1 .LBB0_1069
	s_and_b32 s98, s76, 7
	s_lshr_b32 s99, s76, 3
	s_lshl_b32 s100, s98, 9
	s_or_b32 s100, s100, s99
	s_lshl_b32 s98, s98, 10
	s_add_i32 s98, s98, s99
	s_addk_i32 s98, 0xe00
	s_cmpk_lt_u32 s99, 0x200
	s_cselect_b32 s76, s100, s98
	s_cmpk_gt_i32 s76, 0xfff
	v_lshlrev_b32_e32 v2, 1, v184
	s_cbranch_scc0 .LBB0_1090
	s_add_i32 s40, s76, 0xfffff000
	s_lshr_b32 s40, s40, 10
	s_and_b32 s84, s76, 0x7f
	s_lshl_b32 s41, s40, 12
	s_lshl_b32 s85, s84, 5
	s_or_b32 s41, s41, s85
	v_or_b32_e32 v4, s41, v185
	s_bfe_u32 s82, s76, 0x30007
	v_mul_lo_u32 v4, v4, s59
	v_mov_b32_e32 v5, v3
	v_lshl_add_u64 v[4:5], v[4:5], 1, s[48:49]
	s_lshl_b32 s74, s82, 7
	v_lshl_add_u64 v[100:101], v[4:5], 0, s[74:75]
	s_lshl_b32 s74, s82, 2
	v_mov_b32_e32 v4, s74
	v_lshl_add_u64 v[6:7], v[100:101], 0, v[2:3]
	global_load_dword v8, v4, s[72:73]
	global_load_dwordx4 v[52:55], v[6:7], off
	global_load_dwordx4 v[56:59], v[6:7], off offset:32
	global_load_dwordx4 v[60:63], v[6:7], off offset:64
	global_load_dwordx4 v[64:67], v[6:7], off offset:96
	v_sub_u32_e64 v6, 4, s84 clamp
	s_lshl_b32 s41, s76, 10
	v_add_u32_e32 v6, s84, v6
	s_and_b32 s41, s41, 0x80000
	s_lshl_b32 s40, s40, 20
	v_add_u32_e32 v6, -4, v6
	s_or_b32 s74, s40, s41
	v_ashrrev_i32_e32 v7, 31, v6
	v_lshl_add_u64 v[4:5], v[188:189], 0, s[74:75]
	v_lshlrev_b64 v[6:7], 12, v[6:7]
	v_lshl_add_u64 v[4:5], v[4:5], 0, v[6:7]
	global_load_dwordx4 v[80:83], v[4:5], off offset:3072
	global_load_dwordx4 v[76:79], v[4:5], off offset:2048
	global_load_dwordx4 v[72:75], v[4:5], off offset:1024
	global_load_dwordx4 v[68:71], v[4:5], off
	s_mov_b32 s40, s76
	s_mov_b32 s41, s75
	s_and_b32 s40, s40, 0x7f
	v_and_b32_e32 v9, 64, v1
	s_add_i32 s82, s82, 1
	v_cmp_lt_u64_e64 s[68:69], s[40:41], 4
	v_xor_b32_e32 v7, 32, v1
	v_add_u32_e32 v9, 64, v9
	v_cvt_f32_ubyte0_e32 v10, s82
	s_and_b64 s[68:69], s[68:69], exec
	v_or_b32_e32 v11, s85, v185
	v_cmp_lt_i32_e32 vcc, v7, v9
	v_exp_f32_e64 v9, -v10
	s_cselect_b32 s40, s40, 4
	s_min_u32 s68, s84, 4
	v_cvt_f32_u32_e32 v10, v11
	s_lshl_b32 s77, s40, 12
	s_sub_i32 s40, s84, s68
	s_ashr_i32 s41, s40, 31
	s_add_u32 s82, s77, 0xffffc000
	s_add_u32 s84, s77, 0x1000
	s_lshl_b64 s[40:41], s[40:41], 12
	v_cndmask_b32_e32 v7, v1, v7, vcc
	v_mul_f32_e32 v102, 0x3fb8aa3b, v9
	s_add_u32 s40, s40, s74
	v_mov_b32_e32 v18, v3
	v_mov_b32_e32 v19, v3
	v_mov_b32_e32 v4, v3
	v_mov_b32_e32 v5, v3
	v_mov_b32_e32 v6, v3
	v_lshlrev_b32_e32 v103, 2, v7
	v_mul_f32_e32 v124, v102, v10
	s_addc_u32 s41, s41, 0
	s_lshl_b32 s68, s68, 5
	v_mov_b32_e32 v7, v3
	v_mov_b32_e32 v9, v3
	v_mov_b32_e32 v10, v3
	v_mov_b32_e32 v11, v3
	v_mov_b32_e32 v12, v3
	v_mov_b32_e32 v13, v3
	v_mov_b32_e32 v14, v3
	v_mov_b32_e32 v15, v3
	v_mov_b32_e32 v16, v3
	v_mov_b32_e32 v17, v3
	v_pk_mul_f32 v[104:105], v[102:103], v[190:191] op_sel_hi:[0,1]
	v_pk_mul_f32 v[106:107], v[102:103], v[192:193] op_sel_hi:[0,1]
	v_pk_mul_f32 v[108:109], v[102:103], v[194:195] op_sel_hi:[0,1]
	v_pk_mul_f32 v[110:111], v[102:103], v[196:197] op_sel_hi:[0,1]
	v_pk_mul_f32 v[112:113], v[102:103], v[198:199] op_sel_hi:[0,1]
	v_pk_mul_f32 v[114:115], v[102:103], v[200:201] op_sel_hi:[0,1]
	v_pk_mul_f32 v[116:117], v[102:103], v[202:203] op_sel_hi:[0,1]
	v_pk_mul_f32 v[118:119], v[102:103], v[204:205] op_sel_hi:[0,1]
	v_lshl_add_u64 v[120:121], v[208:209], 0, s[40:41]
	s_sub_i32 s74, s85, s68
	v_lshl_add_u64 v[122:123], v[212:213], 0, s[40:41]
	v_mov_b32_e32 v125, 1.0
	s_mov_b64 s[40:41], 0
	s_waitcnt vmcnt(8)
	v_mul_f32_e32 v126, 0x3fb8aa3b, v8
	v_mov_b32_e32 v8, v3
	v_mov_b64_e32 v[34:35], v[18:19]
	v_mov_b64_e32 v[32:33], v[16:17]
	v_mov_b64_e32 v[30:31], v[14:15]
	v_mov_b64_e32 v[28:29], v[12:13]
	v_mov_b64_e32 v[26:27], v[10:11]
	v_mov_b64_e32 v[24:25], v[8:9]
	v_mov_b64_e32 v[22:23], v[6:7]
	v_mov_b64_e32 v[20:21], v[4:5]
	s_branch .LBB0_1082
